# EpiGLU epilogue: global loads/stores with counted waits (stores younger than the needed loads stay in flight)
# baseline (speedup 1.0000x reference)
; __device__ __forceinline__ unsigned cvt_pk_bf16(float lo, float hi) { f32x2 v = {lo, hi}; bf16x2_t b = __builtin_convertvector(v, bf16x2_t); return __builtin_bit_cast(unsigned, b); }
; __device__ __forceinline__ float bflo(unsigned w) { return __uint_as_float(w << 16); }
; __device__ __forceinline__ float bfhi(unsigned w) { return __uint_as_float(w & 0xffff0000u); }
; __device__ __forceinline__ float sigmoidf_(float v) { return __builtin_amdgcn_rcpf(1.0f + __builtin_amdgcn_exp2f(-1.4426950408889634f * v)); }
;     __device__ __forceinline__ void operator()(const f32x4 (&acc)[2][2][4][2], const Unit& u, int wr, int wc, int fr, int fq) const {
;         f32x4 bv[2][2];
; #pragma unroll
;         for (int bj = 0; bj < 2; ++bj)
; #pragma unroll
;             for (int n = 0; n < 2; ++n) bv[bj][n] = *(const f32x4*)(bglu + 256 * u.pn + 128 * bj + 32 * wc + 8 * fq + 4 * n);
;         const size_t col0 = (size_t)256 * u.pn + 32 * wc + 8 * fq;
;         u32x4 gpre[2][2];
; #pragma unroll
;         for (int bj = 0; bj < 2; ++bj) gpre[0][bj] = *(const u32x4*)(GACT + ((size_t)256 * u.pm + 64 * wr + fr) * 1024 + col0 + 128 * bj);
; #pragma unroll
;         for (int g = 0; g < 8; ++g) {
;             const int ai = g >> 2, m = g & 3;
;             const size_t row = (size_t)256 * u.pm + 128 * ai + 64 * wr + 16 * m + fr;
;             if (g + 1 < 8) {
;                 const size_t rn = (size_t)256 * u.pm + 128 * ((g + 1) >> 2) + 64 * wr + 16 * ((g + 1) & 3) + fr;
; #pragma unroll
;                 for (int bj = 0; bj < 2; ++bj) gpre[(g + 1) & 1][bj] = *(const u32x4*)(GACT + rn * 1024 + col0 + 128 * bj);
;             }
;             asm volatile("" ::: "memory");
; #pragma unroll
;             for (int bj = 0; bj < 2; ++bj) {
;                 const u32x4 gv = gpre[g & 1][bj];
;                 const f32x4 a = acc[ai][bj][m][0] + bv[bj][0], b = acc[ai][bj][m][1] + bv[bj][1];
;                 u32x4 w;
;                 w.x = cvt_pk_bf16(bflo(gv.x) * sigmoidf_(a[0]), bfhi(gv.x) * sigmoidf_(a[1])); w.y = cvt_pk_bf16(bflo(gv.y) * sigmoidf_(a[2]), bfhi(gv.y) * sigmoidf_(a[3]));
;                 w.z = cvt_pk_bf16(bflo(gv.z) * sigmoidf_(b[0]), bfhi(gv.z) * sigmoidf_(b[1])); w.w = cvt_pk_bf16(bflo(gv.w) * sigmoidf_(b[2]), bfhi(gv.w) * sigmoidf_(b[3]));
;                 *(u32x4*)(YB + row * 1024 + col0 + 128 * bj) = w;
.LBB0_387:
	s_lshl_b32 s2, s18, 8
	s_ashr_i32 s3, s2, 31
	v_mov_b32_e32 v40, v173
	v_mov_b32_e32 v136, v172
	s_lshl_b64 s[2:3], s[2:3], 2
	s_add_u32 s2, s11, s2
	v_lshlrev_b32_e32 v138, 3, v40
	s_addc_u32 s3, s10, s3
	v_ashrrev_i32_e32 v139, 31, v138
	s_ashr_i32 s19, s18, 31
	v_lshl_add_u64 v[44:45], v[138:139], 2, s[2:3]
	s_lshl_b64 s[2:3], s[18:19], 8
	v_readlane_b32 s18, v253, 15
	global_load_dwordx4 v[56:59], v[44:45], off offset:16
	global_load_dwordx4 v[60:63], v[44:45], off
	global_load_dwordx4 v[40:43], v[44:45], off offset:528
	s_nop 0
	global_load_dwordx4 v[44:47], v[44:45], off offset:512
	v_readlane_b32 s19, v253, 16
	s_or_b64 s[2:3], s[2:3], s[18:19]
	s_ashr_i32 s17, s16, 31
	v_lshl_add_u64 v[138:139], s[2:3], 0, v[138:139]
	s_lshl_b64 s[2:3], s[16:17], 8
	s_add_u32 s2, s2, s7
	s_addc_u32 s3, s3, s23
	v_ashrrev_i32_e32 v137, 31, v136
	v_lshl_add_u64 v[136:137], s[2:3], 0, v[136:137]
	v_lshlrev_b64 v[168:169], 11, v[136:137]
	v_lshl_add_u64 v[136:137], s[0:1], 0, v[168:169]
	v_lshlrev_b64 v[170:171], 1, v[138:139]
	v_lshl_add_u64 v[166:167], v[136:137], 0, v[170:171]
	global_load_dwordx4 v[176:179], v[166:167], off
	global_load_dwordx4 v[152:155], v[166:167], off offset:256
	s_mov_b32 s13, 0x8000
	s_mov_b64 s[2:3], 0x8000
	v_add_co_u32_e32 v138, vcc, s13, v166
	v_lshl_add_u64 v[136:137], v[166:167], 0, s[2:3]
	s_nop 0
	v_addc_co_u32_e32 v139, vcc, 0, v167, vcc
	global_load_dwordx4 v[140:143], v[138:139], off
	s_nop 0
	global_load_dwordx4 v[136:139], v[136:137], off offset:256
	s_mov_b32 s18, 0x10000
	s_mov_b64 s[16:17], 0x10000
	s_waitcnt vmcnt(0)
	v_pk_add_f32 v[180:181], v[146:147], v[58:59]
	v_pk_add_f32 v[148:149], v[148:149], v[60:61]
	v_pk_add_f32 v[146:147], v[144:145], v[56:57]
	v_mul_f32_e32 v144, 0xbfb8aa3b, v148
	v_mul_f32_e32 v145, 0xbfb8aa3b, v149
	v_exp_f32_e32 v144, v144
	v_exp_f32_e32 v145, v145
	v_pk_add_f32 v[150:151], v[150:151], v[62:63]
	v_mul_f32_e32 v146, 0xbfb8aa3b, v146
	v_add_f32_e32 v144, 1.0, v144
	v_add_f32_e32 v145, 1.0, v145
	v_rcp_f32_e32 v144, v144
	v_rcp_f32_e32 v145, v145
	v_mul_f32_e32 v147, 0xbfb8aa3b, v147
	v_exp_f32_e32 v146, v146
	v_exp_f32_e32 v147, v147
	s_waitcnt lgkmcnt(0)
	v_lshlrev_b32_e32 v148, 16, v176
	v_and_b32_e32 v149, 0xffff0000, v176
	v_pk_mul_f32 v[144:145], v[144:145], v[148:149]
	v_add_f32_e32 v146, 1.0, v146
	v_cvt_pk_bf16_f32 v144, v144, v145
	v_mul_f32_e32 v145, 0xbfb8aa3b, v150
	v_exp_f32_e32 v145, v145
	v_add_f32_e32 v147, 1.0, v147
	v_rcp_f32_e32 v146, v146
	v_rcp_f32_e32 v147, v147
	v_add_f32_e32 v145, 1.0, v145
	v_rcp_f32_e32 v148, v145
	v_mul_f32_e32 v145, 0xbfb8aa3b, v151
	v_exp_f32_e32 v145, v145
	v_lshlrev_b32_e32 v150, 16, v177
	v_and_b32_e32 v151, 0xffff0000, v177
	v_pk_add_f32 v[132:133], v[132:133], v[44:45]
	v_add_f32_e32 v145, 1.0, v145
	v_rcp_f32_e32 v149, v145
	v_mul_f32_e32 v132, 0xbfb8aa3b, v132
	v_mul_f32_e32 v133, 0xbfb8aa3b, v133
	v_exp_f32_e32 v132, v132
	v_pk_mul_f32 v[148:149], v[148:149], v[150:151]
	v_exp_f32_e32 v133, v133
	v_cvt_pk_bf16_f32 v145, v148, v149
	v_lshlrev_b32_e32 v148, 16, v178
	v_and_b32_e32 v149, 0xffff0000, v178
	v_pk_mul_f32 v[146:147], v[146:147], v[148:149]
	v_lshlrev_b32_e32 v150, 16, v179
	v_cvt_pk_bf16_f32 v146, v146, v147
	v_mul_f32_e32 v147, 0xbfb8aa3b, v180
	v_exp_f32_e32 v147, v147
	v_and_b32_e32 v151, 0xffff0000, v179
	v_add_f32_e32 v132, 1.0, v132
	v_add_f32_e32 v133, 1.0, v133
	v_add_f32_e32 v147, 1.0, v147
	v_rcp_f32_e32 v148, v147
	v_mul_f32_e32 v147, 0xbfb8aa3b, v181
	v_exp_f32_e32 v147, v147
	v_rcp_f32_e32 v132, v132
	v_rcp_f32_e32 v133, v133
	v_pk_add_f32 v[134:135], v[134:135], v[46:47]
	v_add_f32_e32 v147, 1.0, v147
	v_rcp_f32_e32 v149, v147
	v_pk_add_f32 v[128:129], v[128:129], v[40:41]
	v_pk_add_f32 v[124:125], v[124:125], v[60:61]
	v_mul_f32_e32 v128, 0xbfb8aa3b, v128
	v_pk_mul_f32 v[148:149], v[148:149], v[150:151]
	v_mul_f32_e32 v129, 0xbfb8aa3b, v129
	v_cvt_pk_bf16_f32 v147, v148, v149
	v_lshl_add_u64 v[148:149], s[8:9], 0, v[168:169]
	v_lshl_add_u64 v[148:149], v[148:149], 0, v[170:171]
	global_store_dwordx4 v[148:149], v[144:147], off
	v_exp_f32_e32 v128, v128
	v_exp_f32_e32 v129, v129
	v_lshlrev_b32_e32 v144, 16, v152
	v_and_b32_e32 v145, 0xffff0000, v152
	v_pk_mul_f32 v[132:133], v[132:133], v[144:145]
	v_add_f32_e32 v128, 1.0, v128
	v_cvt_pk_bf16_f32 v132, v132, v133
	v_mul_f32_e32 v133, 0xbfb8aa3b, v134
	v_exp_f32_e32 v133, v133
	v_add_f32_e32 v129, 1.0, v129
	v_rcp_f32_e32 v128, v128
	v_rcp_f32_e32 v129, v129
	v_add_f32_e32 v133, 1.0, v133
	v_rcp_f32_e32 v134, v133
	v_mul_f32_e32 v133, 0xbfb8aa3b, v135
	v_exp_f32_e32 v133, v133
	v_lshlrev_b32_e32 v144, 16, v153
	v_and_b32_e32 v145, 0xffff0000, v153
	v_pk_add_f32 v[130:131], v[130:131], v[42:43]
	v_add_f32_e32 v133, 1.0, v133
	v_rcp_f32_e32 v135, v133
	v_pk_add_f32 v[126:127], v[126:127], v[62:63]
	v_pk_add_f32 v[116:117], v[116:117], v[44:45]
	v_pk_add_f32 v[118:119], v[118:119], v[46:47]
	v_pk_mul_f32 v[134:135], v[134:135], v[144:145]
	v_pk_add_f32 v[144:145], v[122:123], v[58:59]
	v_cvt_pk_bf16_f32 v133, v134, v135
	v_lshlrev_b32_e32 v134, 16, v154
	v_and_b32_e32 v135, 0xffff0000, v154
	v_pk_mul_f32 v[128:129], v[128:129], v[134:135]
	v_pk_add_f32 v[122:123], v[120:121], v[56:57]
	v_mul_f32_e32 v120, 0xbfb8aa3b, v124
	v_mul_f32_e32 v121, 0xbfb8aa3b, v125
	v_cvt_pk_bf16_f32 v134, v128, v129
	v_mul_f32_e32 v128, 0xbfb8aa3b, v130
	v_mul_f32_e32 v129, 0xbfb8aa3b, v131
	v_exp_f32_e32 v120, v120
	v_exp_f32_e32 v121, v121
	v_exp_f32_e32 v128, v128
	v_exp_f32_e32 v129, v129
	v_add_f32_e32 v120, 1.0, v120
	v_add_f32_e32 v121, 1.0, v121
	v_add_f32_e32 v128, 1.0, v128
	v_add_f32_e32 v129, 1.0, v129
	v_rcp_f32_e32 v120, v120
	v_rcp_f32_e32 v121, v121
; __device__ __forceinline__ unsigned cvt_pk_bf16(float lo, float hi) { f32x2 v = {lo, hi}; bf16x2_t b = __builtin_convertvector(v, bf16x2_t); return __builtin_bit_cast(unsigned, b); }
; __device__ __forceinline__ float bflo(unsigned w) { return __uint_as_float(w << 16); }
; __device__ __forceinline__ float bfhi(unsigned w) { return __uint_as_float(w & 0xffff0000u); }
; __device__ __forceinline__ float sigmoidf_(float v) { return __builtin_amdgcn_rcpf(1.0f + __builtin_amdgcn_exp2f(-1.4426950408889634f * v)); }
;     __device__ __forceinline__ void operator()(const f32x4 (&acc)[2][2][4][2], const Unit& u, int wr, int wc, int fr, int fq) const {
;     ...
;         for (int g = 0; g < 8; ++g) {
;             const int ai = g >> 2, m = g & 3;
;             const size_t row = (size_t)256 * u.pm + 128 * ai + 64 * wr + 16 * m + fr;
;             if (g + 1 < 8) {
;                 const size_t rn = (size_t)256 * u.pm + 128 * ((g + 1) >> 2) + 64 * wr + 16 * ((g + 1) & 3) + fr;
; #pragma unroll
;                 for (int bj = 0; bj < 2; ++bj) gpre[(g + 1) & 1][bj] = *(const u32x4*)(GACT + rn * 1024 + col0 + 128 * bj);
;             }
;             asm volatile("" ::: "memory");
; #pragma unroll
;             for (int bj = 0; bj < 2; ++bj) {
;                 const u32x4 gv = gpre[g & 1][bj];
;                 const f32x4 a = acc[ai][bj][m][0] + bv[bj][0], b = acc[ai][bj][m][1] + bv[bj][1];
;                 u32x4 w;
;                 w.x = cvt_pk_bf16(bflo(gv.x) * sigmoidf_(a[0]), bfhi(gv.x) * sigmoidf_(a[1])); w.y = cvt_pk_bf16(bflo(gv.y) * sigmoidf_(a[2]), bfhi(gv.y) * sigmoidf_(a[3]));
;                 w.z = cvt_pk_bf16(bflo(gv.z) * sigmoidf_(b[0]), bfhi(gv.z) * sigmoidf_(b[1])); w.w = cvt_pk_bf16(bflo(gv.w) * sigmoidf_(b[2]), bfhi(gv.w) * sigmoidf_(b[3]));
;                 *(u32x4*)(YB + row * 1024 + col0 + 128 * bj) = w;
	v_rcp_f32_e32 v128, v128
	v_rcp_f32_e32 v129, v129
	v_lshlrev_b32_e32 v124, 16, v140
	v_and_b32_e32 v125, 0xffff0000, v140
	v_lshlrev_b32_e32 v130, 16, v155
	v_and_b32_e32 v131, 0xffff0000, v155
	v_pk_mul_f32 v[120:121], v[120:121], v[124:125]
	v_pk_mul_f32 v[128:129], v[128:129], v[130:131]
	v_cvt_pk_bf16_f32 v120, v120, v121
	v_mul_f32_e32 v121, 0xbfb8aa3b, v126
	v_cvt_pk_bf16_f32 v135, v128, v129
	v_add_co_u32_e32 v130, vcc, s18, v166
	v_exp_f32_e32 v121, v121
	global_store_dwordx4 v[148:149], v[132:135], off offset:256
	v_lshl_add_u64 v[128:129], v[166:167], 0, s[16:17]
	v_addc_co_u32_e32 v131, vcc, 0, v167, vcc
	global_load_dwordx4 v[132:135], v[130:131], off
	s_nop 0
	global_load_dwordx4 v[128:131], v[128:129], off offset:256
	v_add_f32_e32 v121, 1.0, v121
	v_rcp_f32_e32 v124, v121
	v_mul_f32_e32 v121, 0xbfb8aa3b, v127
	v_exp_f32_e32 v121, v121
	v_mul_f32_e32 v122, 0xbfb8aa3b, v122
	v_mul_f32_e32 v123, 0xbfb8aa3b, v123
	v_exp_f32_e32 v122, v122
	v_exp_f32_e32 v123, v123
	v_add_f32_e32 v121, 1.0, v121
	v_rcp_f32_e32 v125, v121
	v_add_f32_e32 v122, 1.0, v122
	v_add_f32_e32 v123, 1.0, v123
	v_rcp_f32_e32 v122, v122
	v_rcp_f32_e32 v123, v123
	v_lshlrev_b32_e32 v126, 16, v141
	v_and_b32_e32 v127, 0xffff0000, v141
	v_pk_mul_f32 v[124:125], v[124:125], v[126:127]
	v_lshlrev_b32_e32 v126, 16, v143
	v_cvt_pk_bf16_f32 v121, v124, v125
	v_lshlrev_b32_e32 v124, 16, v142
	v_and_b32_e32 v125, 0xffff0000, v142
	v_pk_mul_f32 v[122:123], v[122:123], v[124:125]
	v_and_b32_e32 v127, 0xffff0000, v143
	v_cvt_pk_bf16_f32 v122, v122, v123
	v_mul_f32_e32 v123, 0xbfb8aa3b, v144
	v_exp_f32_e32 v123, v123
	v_pk_add_f32 v[108:109], v[108:109], v[60:61]
	v_pk_add_f32 v[110:111], v[110:111], v[62:63]
	v_add_f32_e32 v123, 1.0, v123
	v_rcp_f32_e32 v124, v123
	v_mul_f32_e32 v123, 0xbfb8aa3b, v145
	v_exp_f32_e32 v123, v123
	v_pk_add_f32 v[100:101], v[100:101], v[44:45]
	v_pk_add_f32 v[102:103], v[102:103], v[46:47]
	v_pk_add_f32 v[92:93], v[92:93], v[60:61]
	v_add_f32_e32 v123, 1.0, v123
	v_rcp_f32_e32 v125, v123
	v_pk_add_f32 v[94:95], v[94:95], v[62:63]
	v_pk_add_f32 v[84:85], v[84:85], v[44:45]
	v_pk_add_f32 v[86:87], v[86:87], v[46:47]
	v_pk_mul_f32 v[124:125], v[124:125], v[126:127]
	v_add_co_u32_e32 v126, vcc, s13, v148
	v_cvt_pk_bf16_f32 v123, v124, v125
	s_nop 0
	v_addc_co_u32_e32 v127, vcc, 0, v149, vcc
	global_store_dwordx4 v[126:127], v[120:123], off
	v_lshl_add_u64 v[124:125], v[148:149], 0, s[2:3]
	s_mov_b32 s13, 0x18000
	v_pk_add_f32 v[120:121], v[114:115], v[42:43]
	v_pk_add_f32 v[114:115], v[112:113], v[40:41]
	v_mul_f32_e32 v112, 0xbfb8aa3b, v116
	v_mul_f32_e32 v113, 0xbfb8aa3b, v117
	v_exp_f32_e32 v112, v112
	v_exp_f32_e32 v113, v113
	v_lshlrev_b32_e32 v116, 16, v136
	v_and_b32_e32 v117, 0xffff0000, v136
	v_add_f32_e32 v112, 1.0, v112
	v_add_f32_e32 v113, 1.0, v113
	v_rcp_f32_e32 v112, v112
	v_rcp_f32_e32 v113, v113
	v_mul_f32_e32 v114, 0xbfb8aa3b, v114
	v_mul_f32_e32 v115, 0xbfb8aa3b, v115
	v_exp_f32_e32 v114, v114
	v_pk_mul_f32 v[112:113], v[112:113], v[116:117]
	v_exp_f32_e32 v115, v115
	v_cvt_pk_bf16_f32 v112, v112, v113
	v_mul_f32_e32 v113, 0xbfb8aa3b, v118
	v_exp_f32_e32 v113, v113
	v_add_f32_e32 v114, 1.0, v114
	v_add_f32_e32 v115, 1.0, v115
	v_rcp_f32_e32 v114, v114
	v_add_f32_e32 v113, 1.0, v113
	v_rcp_f32_e32 v116, v113
	v_mul_f32_e32 v113, 0xbfb8aa3b, v119
	v_exp_f32_e32 v113, v113
	v_rcp_f32_e32 v115, v115
	v_lshlrev_b32_e32 v118, 16, v137
	v_and_b32_e32 v119, 0xffff0000, v137
	v_add_f32_e32 v113, 1.0, v113
	v_rcp_f32_e32 v117, v113
	s_mov_b64 s[2:3], 0x18000
	v_pk_add_f32 v[76:77], v[76:77], v[60:61]
	v_pk_add_f32 v[78:79], v[78:79], v[62:63]
	v_pk_mul_f32 v[116:117], v[116:117], v[118:119]
	v_lshlrev_b32_e32 v118, 16, v139
	v_cvt_pk_bf16_f32 v113, v116, v117
	v_lshlrev_b32_e32 v116, 16, v138
	v_and_b32_e32 v117, 0xffff0000, v138
	v_pk_mul_f32 v[114:115], v[114:115], v[116:117]
	v_and_b32_e32 v119, 0xffff0000, v139
	v_cvt_pk_bf16_f32 v114, v114, v115
	v_mul_f32_e32 v115, 0xbfb8aa3b, v120
	v_exp_f32_e32 v115, v115
	v_pk_add_f32 v[68:69], v[68:69], v[44:45]
	v_pk_add_f32 v[70:71], v[70:71], v[46:47]
	v_pk_add_f32 v[52:53], v[52:53], v[60:61]
	v_add_f32_e32 v115, 1.0, v115
	v_rcp_f32_e32 v116, v115
	v_mul_f32_e32 v115, 0xbfb8aa3b, v121
	v_pk_add_f32 v[120:121], v[106:107], v[58:59]
	v_pk_add_f32 v[106:107], v[104:105], v[56:57]
	v_mul_f32_e32 v104, 0xbfb8aa3b, v108
	v_mul_f32_e32 v105, 0xbfb8aa3b, v109
	v_exp_f32_e32 v115, v115
	v_exp_f32_e32 v104, v104
	v_exp_f32_e32 v105, v105
	s_waitcnt vmcnt(1) lgkmcnt(0)
; __device__ __forceinline__ unsigned cvt_pk_bf16(float lo, float hi) { f32x2 v = {lo, hi}; bf16x2_t b = __builtin_convertvector(v, bf16x2_t); return __builtin_bit_cast(unsigned, b); }
; __device__ __forceinline__ float bflo(unsigned w) { return __uint_as_float(w << 16); }
; __device__ __forceinline__ float bfhi(unsigned w) { return __uint_as_float(w & 0xffff0000u); }
; __device__ __forceinline__ float sigmoidf_(float v) { return __builtin_amdgcn_rcpf(1.0f + __builtin_amdgcn_exp2f(-1.4426950408889634f * v)); }
;     __device__ __forceinline__ void operator()(const f32x4 (&acc)[2][2][4][2], const Unit& u, int wr, int wc, int fr, int fq) const {
;     ...
;         for (int g = 0; g < 8; ++g) {
;             const int ai = g >> 2, m = g & 3;
;             const size_t row = (size_t)256 * u.pm + 128 * ai + 64 * wr + 16 * m + fr;
;             if (g + 1 < 8) {
;                 const size_t rn = (size_t)256 * u.pm + 128 * ((g + 1) >> 2) + 64 * wr + 16 * ((g + 1) & 3) + fr;
; #pragma unroll
;                 for (int bj = 0; bj < 2; ++bj) gpre[(g + 1) & 1][bj] = *(const u32x4*)(GACT + rn * 1024 + col0 + 128 * bj);
;             }
;             asm volatile("" ::: "memory");
; #pragma unroll
;             for (int bj = 0; bj < 2; ++bj) {
;                 const u32x4 gv = gpre[g & 1][bj];
;                 const f32x4 a = acc[ai][bj][m][0] + bv[bj][0], b = acc[ai][bj][m][1] + bv[bj][1];
;                 u32x4 w;
;                 w.x = cvt_pk_bf16(bflo(gv.x) * sigmoidf_(a[0]), bfhi(gv.x) * sigmoidf_(a[1])); w.y = cvt_pk_bf16(bflo(gv.y) * sigmoidf_(a[2]), bfhi(gv.y) * sigmoidf_(a[3]));
;                 w.z = cvt_pk_bf16(bflo(gv.z) * sigmoidf_(b[0]), bfhi(gv.z) * sigmoidf_(b[1])); w.w = cvt_pk_bf16(bflo(gv.w) * sigmoidf_(b[2]), bfhi(gv.w) * sigmoidf_(b[3]));
;                 *(u32x4*)(YB + row * 1024 + col0 + 128 * bj) = w;
	v_lshlrev_b32_e32 v108, 16, v132
	v_add_f32_e32 v115, 1.0, v115
	v_add_f32_e32 v104, 1.0, v104
	v_add_f32_e32 v105, 1.0, v105
	v_rcp_f32_e32 v117, v115
	v_rcp_f32_e32 v104, v104
	v_rcp_f32_e32 v105, v105
	v_and_b32_e32 v109, 0xffff0000, v132
	v_pk_mul_f32 v[116:117], v[116:117], v[118:119]
	v_mul_f32_e32 v106, 0xbfb8aa3b, v106
	v_pk_mul_f32 v[104:105], v[104:105], v[108:109]
	v_cvt_pk_bf16_f32 v115, v116, v117
	v_cvt_pk_bf16_f32 v104, v104, v105
	v_mul_f32_e32 v105, 0xbfb8aa3b, v110
	global_store_dwordx4 v[124:125], v[112:115], off offset:256
	v_exp_f32_e32 v105, v105
	v_mul_f32_e32 v107, 0xbfb8aa3b, v107
	v_add_co_u32_e32 v114, vcc, s13, v166
	v_lshl_add_u64 v[112:113], v[166:167], 0, s[2:3]
	s_nop 0
	v_addc_co_u32_e32 v115, vcc, 0, v167, vcc
	global_load_dwordx4 v[116:119], v[114:115], off
	s_nop 0
	global_load_dwordx4 v[112:115], v[112:113], off offset:256
	v_add_f32_e32 v105, 1.0, v105
	v_rcp_f32_e32 v108, v105
	v_mul_f32_e32 v105, 0xbfb8aa3b, v111
	v_exp_f32_e32 v105, v105
	v_exp_f32_e32 v106, v106
	v_exp_f32_e32 v107, v107
	v_lshlrev_b32_e32 v110, 16, v133
	v_add_f32_e32 v105, 1.0, v105
	v_rcp_f32_e32 v109, v105
	v_add_f32_e32 v106, 1.0, v106
	v_add_f32_e32 v107, 1.0, v107
	v_rcp_f32_e32 v106, v106
	v_rcp_f32_e32 v107, v107
	v_and_b32_e32 v111, 0xffff0000, v133
	v_pk_mul_f32 v[108:109], v[108:109], v[110:111]
	v_lshlrev_b32_e32 v110, 16, v135
	v_cvt_pk_bf16_f32 v105, v108, v109
	v_lshlrev_b32_e32 v108, 16, v134
	v_and_b32_e32 v109, 0xffff0000, v134
	v_pk_mul_f32 v[106:107], v[106:107], v[108:109]
	v_and_b32_e32 v111, 0xffff0000, v135
	v_cvt_pk_bf16_f32 v106, v106, v107
	v_mul_f32_e32 v107, 0xbfb8aa3b, v120
	v_exp_f32_e32 v107, v107
	v_pk_add_f32 v[54:55], v[54:55], v[62:63]
	v_pk_add_f32 v[36:37], v[36:37], v[44:45]
	v_add_f32_e32 v107, 1.0, v107
	v_rcp_f32_e32 v108, v107
	v_mul_f32_e32 v107, 0xbfb8aa3b, v121
	v_exp_f32_e32 v107, v107
	v_pk_add_f32 v[38:39], v[38:39], v[46:47]
	v_pk_add_f32 v[28:29], v[28:29], v[60:61]
	v_pk_add_f32 v[30:31], v[30:31], v[62:63]
	v_add_f32_e32 v107, 1.0, v107
	v_rcp_f32_e32 v109, v107
	v_pk_add_f32 v[20:21], v[20:21], v[44:45]
	v_pk_add_f32 v[22:23], v[22:23], v[46:47]
	v_pk_add_f32 v[12:13], v[12:13], v[60:61]
	v_pk_mul_f32 v[108:109], v[108:109], v[110:111]
	v_add_co_u32_e32 v110, vcc, s18, v148
	v_cvt_pk_bf16_f32 v107, v108, v109
	s_nop 0
	v_addc_co_u32_e32 v111, vcc, 0, v149, vcc
	global_store_dwordx4 v[110:111], v[104:107], off
	v_lshl_add_u64 v[108:109], v[148:149], 0, s[16:17]
	s_mov_b64 s[16:17], 0x40000
	v_pk_add_f32 v[104:105], v[98:99], v[42:43]
	v_pk_add_f32 v[98:99], v[96:97], v[40:41]
	v_mul_f32_e32 v96, 0xbfb8aa3b, v100
	v_mul_f32_e32 v97, 0xbfb8aa3b, v101
	v_exp_f32_e32 v96, v96
	v_exp_f32_e32 v97, v97
	v_lshlrev_b32_e32 v100, 16, v128
	v_and_b32_e32 v101, 0xffff0000, v128
	v_add_f32_e32 v96, 1.0, v96
	v_add_f32_e32 v97, 1.0, v97
	v_rcp_f32_e32 v96, v96
	v_rcp_f32_e32 v97, v97
	v_mul_f32_e32 v98, 0xbfb8aa3b, v98
	v_mul_f32_e32 v99, 0xbfb8aa3b, v99
	v_exp_f32_e32 v98, v98
	v_pk_mul_f32 v[96:97], v[96:97], v[100:101]
	v_exp_f32_e32 v99, v99
	v_cvt_pk_bf16_f32 v96, v96, v97
	v_mul_f32_e32 v97, 0xbfb8aa3b, v102
	v_exp_f32_e32 v97, v97
	v_add_f32_e32 v98, 1.0, v98
	v_add_f32_e32 v99, 1.0, v99
	v_rcp_f32_e32 v98, v98
	v_add_f32_e32 v97, 1.0, v97
	v_rcp_f32_e32 v100, v97
	v_mul_f32_e32 v97, 0xbfb8aa3b, v103
	v_exp_f32_e32 v97, v97
	v_rcp_f32_e32 v99, v99
	v_lshlrev_b32_e32 v102, 16, v129
	v_and_b32_e32 v103, 0xffff0000, v129
	v_add_f32_e32 v97, 1.0, v97
	v_rcp_f32_e32 v101, v97
	s_mov_b64 s[18:19], 0x48000
	v_pk_add_f32 v[14:15], v[14:15], v[62:63]
	v_pk_add_f32 v[4:5], v[4:5], v[44:45]
	v_pk_mul_f32 v[100:101], v[100:101], v[102:103]
	v_lshlrev_b32_e32 v102, 16, v131
	v_cvt_pk_bf16_f32 v97, v100, v101
	v_lshlrev_b32_e32 v100, 16, v130
	v_and_b32_e32 v101, 0xffff0000, v130
	v_pk_mul_f32 v[98:99], v[98:99], v[100:101]
	v_and_b32_e32 v103, 0xffff0000, v131
	v_cvt_pk_bf16_f32 v98, v98, v99
	v_mul_f32_e32 v99, 0xbfb8aa3b, v104
	v_exp_f32_e32 v99, v99
	v_pk_add_f32 v[6:7], v[6:7], v[46:47]
	v_add_f32_e32 v99, 1.0, v99
	v_rcp_f32_e32 v100, v99
	v_mul_f32_e32 v99, 0xbfb8aa3b, v105
	v_pk_add_f32 v[104:105], v[90:91], v[58:59]
	v_pk_add_f32 v[90:91], v[88:89], v[56:57]
	v_mul_f32_e32 v88, 0xbfb8aa3b, v92
	v_mul_f32_e32 v89, 0xbfb8aa3b, v93
	v_exp_f32_e32 v99, v99
	v_exp_f32_e32 v88, v88
	v_exp_f32_e32 v89, v89
	s_waitcnt vmcnt(1) lgkmcnt(0)
; __device__ __forceinline__ unsigned cvt_pk_bf16(float lo, float hi) { f32x2 v = {lo, hi}; bf16x2_t b = __builtin_convertvector(v, bf16x2_t); return __builtin_bit_cast(unsigned, b); }
; __device__ __forceinline__ float bflo(unsigned w) { return __uint_as_float(w << 16); }
; __device__ __forceinline__ float bfhi(unsigned w) { return __uint_as_float(w & 0xffff0000u); }
; __device__ __forceinline__ float sigmoidf_(float v) { return __builtin_amdgcn_rcpf(1.0f + __builtin_amdgcn_exp2f(-1.4426950408889634f * v)); }
;     __device__ __forceinline__ void operator()(const f32x4 (&acc)[2][2][4][2], const Unit& u, int wr, int wc, int fr, int fq) const {
;     ...
;         for (int g = 0; g < 8; ++g) {
;             const int ai = g >> 2, m = g & 3;
;             const size_t row = (size_t)256 * u.pm + 128 * ai + 64 * wr + 16 * m + fr;
;             if (g + 1 < 8) {
;                 const size_t rn = (size_t)256 * u.pm + 128 * ((g + 1) >> 2) + 64 * wr + 16 * ((g + 1) & 3) + fr;
; #pragma unroll
;                 for (int bj = 0; bj < 2; ++bj) gpre[(g + 1) & 1][bj] = *(const u32x4*)(GACT + rn * 1024 + col0 + 128 * bj);
;             }
;             asm volatile("" ::: "memory");
; #pragma unroll
;             for (int bj = 0; bj < 2; ++bj) {
;                 const u32x4 gv = gpre[g & 1][bj];
;                 const f32x4 a = acc[ai][bj][m][0] + bv[bj][0], b = acc[ai][bj][m][1] + bv[bj][1];
;                 u32x4 w;
;                 w.x = cvt_pk_bf16(bflo(gv.x) * sigmoidf_(a[0]), bfhi(gv.x) * sigmoidf_(a[1])); w.y = cvt_pk_bf16(bflo(gv.y) * sigmoidf_(a[2]), bfhi(gv.y) * sigmoidf_(a[3]));
;                 w.z = cvt_pk_bf16(bflo(gv.z) * sigmoidf_(b[0]), bfhi(gv.z) * sigmoidf_(b[1])); w.w = cvt_pk_bf16(bflo(gv.w) * sigmoidf_(b[2]), bfhi(gv.w) * sigmoidf_(b[3]));
;                 *(u32x4*)(YB + row * 1024 + col0 + 128 * bj) = w;
	v_lshlrev_b32_e32 v92, 16, v116
	v_add_f32_e32 v99, 1.0, v99
	v_add_f32_e32 v88, 1.0, v88
	v_add_f32_e32 v89, 1.0, v89
	v_rcp_f32_e32 v101, v99
	v_rcp_f32_e32 v88, v88
	v_rcp_f32_e32 v89, v89
	v_and_b32_e32 v93, 0xffff0000, v116
	v_pk_mul_f32 v[100:101], v[100:101], v[102:103]
	v_mul_f32_e32 v90, 0xbfb8aa3b, v90
	v_pk_mul_f32 v[88:89], v[88:89], v[92:93]
	v_cvt_pk_bf16_f32 v99, v100, v101
	v_cvt_pk_bf16_f32 v88, v88, v89
	v_mul_f32_e32 v89, 0xbfb8aa3b, v94
	global_store_dwordx4 v[108:109], v[96:99], off offset:256
	v_exp_f32_e32 v89, v89
	v_mul_f32_e32 v91, 0xbfb8aa3b, v91
	v_add_co_u32_e32 v98, vcc, s33, v166
	v_lshl_add_u64 v[96:97], v[166:167], 0, s[16:17]
	s_nop 0
	v_addc_co_u32_e32 v99, vcc, 0, v167, vcc
	global_load_dwordx4 v[100:103], v[98:99], off
	s_nop 0
	global_load_dwordx4 v[96:99], v[96:97], off offset:256
	v_add_f32_e32 v89, 1.0, v89
	v_rcp_f32_e32 v92, v89
	v_mul_f32_e32 v89, 0xbfb8aa3b, v95
	v_exp_f32_e32 v89, v89
	v_exp_f32_e32 v90, v90
	v_exp_f32_e32 v91, v91
	v_lshlrev_b32_e32 v94, 16, v117
	v_add_f32_e32 v89, 1.0, v89
	v_rcp_f32_e32 v93, v89
	v_add_f32_e32 v90, 1.0, v90
	v_add_f32_e32 v91, 1.0, v91
	v_rcp_f32_e32 v90, v90
	v_rcp_f32_e32 v91, v91
	v_and_b32_e32 v95, 0xffff0000, v117
	v_pk_mul_f32 v[92:93], v[92:93], v[94:95]
	v_lshlrev_b32_e32 v94, 16, v119
	v_cvt_pk_bf16_f32 v89, v92, v93
	v_lshlrev_b32_e32 v92, 16, v118
	v_and_b32_e32 v93, 0xffff0000, v118
	v_pk_mul_f32 v[90:91], v[90:91], v[92:93]
	v_and_b32_e32 v95, 0xffff0000, v119
	v_cvt_pk_bf16_f32 v90, v90, v91
	v_mul_f32_e32 v91, 0xbfb8aa3b, v104
	v_exp_f32_e32 v91, v91
	s_nop 0
	v_add_f32_e32 v91, 1.0, v91
	v_rcp_f32_e32 v92, v91
	v_mul_f32_e32 v91, 0xbfb8aa3b, v105
	v_exp_f32_e32 v91, v91
	s_nop 0
	v_add_f32_e32 v91, 1.0, v91
	v_rcp_f32_e32 v93, v91
	s_nop 0
	v_pk_mul_f32 v[92:93], v[92:93], v[94:95]
	v_add_co_u32_e32 v94, vcc, s13, v148
	v_cvt_pk_bf16_f32 v91, v92, v93
	s_nop 0
	v_addc_co_u32_e32 v95, vcc, 0, v149, vcc
	global_store_dwordx4 v[94:95], v[88:91], off
	v_lshl_add_u64 v[92:93], v[148:149], 0, s[2:3]
	s_mov_b32 s2, 0x48000
	v_pk_add_f32 v[88:89], v[82:83], v[42:43]
	v_pk_add_f32 v[82:83], v[80:81], v[40:41]
	v_mul_f32_e32 v80, 0xbfb8aa3b, v84
	v_mul_f32_e32 v81, 0xbfb8aa3b, v85
	v_exp_f32_e32 v80, v80
	v_exp_f32_e32 v81, v81
	v_lshlrev_b32_e32 v84, 16, v112
	v_and_b32_e32 v85, 0xffff0000, v112
	v_add_f32_e32 v80, 1.0, v80
	v_add_f32_e32 v81, 1.0, v81
	v_rcp_f32_e32 v80, v80
	v_rcp_f32_e32 v81, v81
	v_mul_f32_e32 v82, 0xbfb8aa3b, v82
	v_mul_f32_e32 v83, 0xbfb8aa3b, v83
	v_exp_f32_e32 v82, v82
	v_pk_mul_f32 v[80:81], v[80:81], v[84:85]
	v_exp_f32_e32 v83, v83
	v_cvt_pk_bf16_f32 v80, v80, v81
	v_mul_f32_e32 v81, 0xbfb8aa3b, v86
	v_exp_f32_e32 v81, v81
	v_add_f32_e32 v82, 1.0, v82
	v_add_f32_e32 v83, 1.0, v83
	v_rcp_f32_e32 v82, v82
	v_add_f32_e32 v81, 1.0, v81
	v_rcp_f32_e32 v84, v81
	v_mul_f32_e32 v81, 0xbfb8aa3b, v87
	v_exp_f32_e32 v81, v81
	v_rcp_f32_e32 v83, v83
	v_lshlrev_b32_e32 v86, 16, v113
	v_and_b32_e32 v87, 0xffff0000, v113
	v_add_f32_e32 v81, 1.0, v81
	v_rcp_f32_e32 v85, v81
	s_mov_b32 s3, 0x50000
	v_pk_mul_f32 v[84:85], v[84:85], v[86:87]
	s_nop 0
	v_cvt_pk_bf16_f32 v81, v84, v85
	v_lshlrev_b32_e32 v84, 16, v114
	v_and_b32_e32 v85, 0xffff0000, v114
	v_pk_mul_f32 v[82:83], v[82:83], v[84:85]
	v_lshlrev_b32_e32 v86, 16, v115
	v_cvt_pk_bf16_f32 v82, v82, v83
	v_mul_f32_e32 v83, 0xbfb8aa3b, v88
	v_exp_f32_e32 v83, v83
	v_and_b32_e32 v87, 0xffff0000, v115
	v_add_f32_e32 v83, 1.0, v83
	v_rcp_f32_e32 v84, v83
	v_mul_f32_e32 v83, 0xbfb8aa3b, v89
	v_pk_add_f32 v[88:89], v[74:75], v[58:59]
	v_pk_add_f32 v[74:75], v[72:73], v[56:57]
	v_mul_f32_e32 v72, 0xbfb8aa3b, v76
	v_mul_f32_e32 v73, 0xbfb8aa3b, v77
	v_exp_f32_e32 v83, v83
	v_exp_f32_e32 v72, v72
	v_exp_f32_e32 v73, v73
	s_waitcnt vmcnt(1) lgkmcnt(0)
	v_lshlrev_b32_e32 v76, 16, v100
	v_add_f32_e32 v83, 1.0, v83
	v_add_f32_e32 v72, 1.0, v72
	v_add_f32_e32 v73, 1.0, v73
	v_rcp_f32_e32 v85, v83
	v_rcp_f32_e32 v72, v72
	v_rcp_f32_e32 v73, v73
	v_and_b32_e32 v77, 0xffff0000, v100
	v_pk_mul_f32 v[84:85], v[84:85], v[86:87]
	v_mul_f32_e32 v74, 0xbfb8aa3b, v74
	v_pk_mul_f32 v[72:73], v[72:73], v[76:77]
	v_cvt_pk_bf16_f32 v83, v84, v85
	v_cvt_pk_bf16_f32 v72, v72, v73
	v_mul_f32_e32 v73, 0xbfb8aa3b, v78
	global_store_dwordx4 v[92:93], v[80:83], off offset:256
	v_exp_f32_e32 v73, v73
	v_mul_f32_e32 v75, 0xbfb8aa3b, v75
	v_add_co_u32_e32 v82, vcc, s2, v166
	v_lshl_add_u64 v[80:81], v[166:167], 0, s[18:19]
	s_nop 0
	v_addc_co_u32_e32 v83, vcc, 0, v167, vcc
	global_load_dwordx4 v[84:87], v[82:83], off
	s_nop 0
	global_load_dwordx4 v[80:83], v[80:81], off offset:256
	v_add_f32_e32 v73, 1.0, v73
	v_rcp_f32_e32 v76, v73
	v_mul_f32_e32 v73, 0xbfb8aa3b, v79
	v_exp_f32_e32 v73, v73
	v_exp_f32_e32 v74, v74
	v_exp_f32_e32 v75, v75
	v_lshlrev_b32_e32 v78, 16, v101
	v_add_f32_e32 v73, 1.0, v73
	v_rcp_f32_e32 v77, v73
	v_add_f32_e32 v74, 1.0, v74
	v_add_f32_e32 v75, 1.0, v75
	v_rcp_f32_e32 v74, v74
	v_rcp_f32_e32 v75, v75
	v_and_b32_e32 v79, 0xffff0000, v101
	v_pk_mul_f32 v[76:77], v[76:77], v[78:79]
	v_lshlrev_b32_e32 v78, 16, v103
	v_cvt_pk_bf16_f32 v73, v76, v77
	v_lshlrev_b32_e32 v76, 16, v102
	v_and_b32_e32 v77, 0xffff0000, v102
	v_pk_mul_f32 v[74:75], v[74:75], v[76:77]
	v_and_b32_e32 v79, 0xffff0000, v103
	v_cvt_pk_bf16_f32 v74, v74, v75
	v_mul_f32_e32 v75, 0xbfb8aa3b, v88
	v_exp_f32_e32 v75, v75
	s_nop 0
	v_add_f32_e32 v75, 1.0, v75
	v_rcp_f32_e32 v76, v75
	v_mul_f32_e32 v75, 0xbfb8aa3b, v89
	v_exp_f32_e32 v75, v75
	s_nop 0
	v_add_f32_e32 v75, 1.0, v75
	v_rcp_f32_e32 v77, v75
	s_nop 0
	v_pk_mul_f32 v[76:77], v[76:77], v[78:79]
	v_add_co_u32_e32 v78, vcc, s33, v148
	v_cvt_pk_bf16_f32 v75, v76, v77
	s_nop 0
; __device__ __forceinline__ unsigned cvt_pk_bf16(float lo, float hi) { f32x2 v = {lo, hi}; bf16x2_t b = __builtin_convertvector(v, bf16x2_t); return __builtin_bit_cast(unsigned, b); }
; __device__ __forceinline__ float bflo(unsigned w) { return __uint_as_float(w << 16); }
; __device__ __forceinline__ float bfhi(unsigned w) { return __uint_as_float(w & 0xffff0000u); }
; __device__ __forceinline__ float sigmoidf_(float v) { return __builtin_amdgcn_rcpf(1.0f + __builtin_amdgcn_exp2f(-1.4426950408889634f * v)); }
;     __device__ __forceinline__ void operator()(const f32x4 (&acc)[2][2][4][2], const Unit& u, int wr, int wc, int fr, int fq) const {
;     ...
;         for (int g = 0; g < 8; ++g) {
;             const int ai = g >> 2, m = g & 3;
;             const size_t row = (size_t)256 * u.pm + 128 * ai + 64 * wr + 16 * m + fr;
;             if (g + 1 < 8) {
;                 const size_t rn = (size_t)256 * u.pm + 128 * ((g + 1) >> 2) + 64 * wr + 16 * ((g + 1) & 3) + fr;
; #pragma unroll
;                 for (int bj = 0; bj < 2; ++bj) gpre[(g + 1) & 1][bj] = *(const u32x4*)(GACT + rn * 1024 + col0 + 128 * bj);
;             }
;             asm volatile("" ::: "memory");
; #pragma unroll
;             for (int bj = 0; bj < 2; ++bj) {
;                 const u32x4 gv = gpre[g & 1][bj];
;                 const f32x4 a = acc[ai][bj][m][0] + bv[bj][0], b = acc[ai][bj][m][1] + bv[bj][1];
;                 u32x4 w;
;                 w.x = cvt_pk_bf16(bflo(gv.x) * sigmoidf_(a[0]), bfhi(gv.x) * sigmoidf_(a[1])); w.y = cvt_pk_bf16(bflo(gv.y) * sigmoidf_(a[2]), bfhi(gv.y) * sigmoidf_(a[3]));
;                 w.z = cvt_pk_bf16(bflo(gv.z) * sigmoidf_(b[0]), bfhi(gv.z) * sigmoidf_(b[1])); w.w = cvt_pk_bf16(bflo(gv.w) * sigmoidf_(b[2]), bfhi(gv.w) * sigmoidf_(b[3]));
;                 *(u32x4*)(YB + row * 1024 + col0 + 128 * bj) = w;
	v_addc_co_u32_e32 v79, vcc, 0, v149, vcc
	global_store_dwordx4 v[78:79], v[72:75], off
	v_lshl_add_u64 v[76:77], v[148:149], 0, s[16:17]
	s_mov_b64 s[16:17], 0x50000
	v_pk_add_f32 v[72:73], v[66:67], v[42:43]
	v_pk_add_f32 v[66:67], v[64:65], v[40:41]
	v_mul_f32_e32 v64, 0xbfb8aa3b, v68
	v_mul_f32_e32 v65, 0xbfb8aa3b, v69
	v_exp_f32_e32 v64, v64
	v_exp_f32_e32 v65, v65
	v_lshlrev_b32_e32 v68, 16, v96
	v_and_b32_e32 v69, 0xffff0000, v96
	v_add_f32_e32 v64, 1.0, v64
	v_add_f32_e32 v65, 1.0, v65
	v_rcp_f32_e32 v64, v64
	v_rcp_f32_e32 v65, v65
	v_mul_f32_e32 v66, 0xbfb8aa3b, v66
	v_mul_f32_e32 v67, 0xbfb8aa3b, v67
	v_exp_f32_e32 v66, v66
	v_pk_mul_f32 v[64:65], v[64:65], v[68:69]
	v_exp_f32_e32 v67, v67
	v_cvt_pk_bf16_f32 v64, v64, v65
	v_mul_f32_e32 v65, 0xbfb8aa3b, v70
	v_exp_f32_e32 v65, v65
	v_add_f32_e32 v66, 1.0, v66
	v_add_f32_e32 v67, 1.0, v67
	v_rcp_f32_e32 v66, v66
	v_add_f32_e32 v65, 1.0, v65
	v_rcp_f32_e32 v68, v65
	v_mul_f32_e32 v65, 0xbfb8aa3b, v71
	v_exp_f32_e32 v65, v65
	v_rcp_f32_e32 v67, v67
	v_lshlrev_b32_e32 v70, 16, v97
	v_and_b32_e32 v71, 0xffff0000, v97
	v_add_f32_e32 v65, 1.0, v65
	v_rcp_f32_e32 v69, v65
	s_nop 0
	v_pk_mul_f32 v[68:69], v[68:69], v[70:71]
	s_nop 0
	v_cvt_pk_bf16_f32 v65, v68, v69
	v_lshlrev_b32_e32 v68, 16, v98
	v_and_b32_e32 v69, 0xffff0000, v98
	v_pk_mul_f32 v[66:67], v[66:67], v[68:69]
	v_lshlrev_b32_e32 v70, 16, v99
	v_cvt_pk_bf16_f32 v66, v66, v67
	v_mul_f32_e32 v67, 0xbfb8aa3b, v72
	v_exp_f32_e32 v67, v67
	v_and_b32_e32 v71, 0xffff0000, v99
	v_add_f32_e32 v67, 1.0, v67
	v_rcp_f32_e32 v68, v67
	v_mul_f32_e32 v67, 0xbfb8aa3b, v73
	v_pk_add_f32 v[72:73], v[50:51], v[58:59]
	v_pk_add_f32 v[50:51], v[48:49], v[56:57]
	v_mul_f32_e32 v48, 0xbfb8aa3b, v52
	v_mul_f32_e32 v49, 0xbfb8aa3b, v53
	v_exp_f32_e32 v67, v67
	v_exp_f32_e32 v48, v48
	v_exp_f32_e32 v49, v49
	s_waitcnt vmcnt(1) lgkmcnt(0)
	v_lshlrev_b32_e32 v52, 16, v84
	v_add_f32_e32 v67, 1.0, v67
	v_add_f32_e32 v48, 1.0, v48
	v_add_f32_e32 v49, 1.0, v49
	v_rcp_f32_e32 v69, v67
	v_rcp_f32_e32 v48, v48
	v_rcp_f32_e32 v49, v49
	v_and_b32_e32 v53, 0xffff0000, v84
	v_pk_mul_f32 v[68:69], v[68:69], v[70:71]
	v_mul_f32_e32 v50, 0xbfb8aa3b, v50
	v_pk_mul_f32 v[48:49], v[48:49], v[52:53]
	v_cvt_pk_bf16_f32 v67, v68, v69
	v_cvt_pk_bf16_f32 v48, v48, v49
	v_mul_f32_e32 v49, 0xbfb8aa3b, v54
	global_store_dwordx4 v[76:77], v[64:67], off offset:256
	v_exp_f32_e32 v49, v49
	v_mul_f32_e32 v51, 0xbfb8aa3b, v51
	v_add_co_u32_e32 v66, vcc, s3, v166
	v_lshl_add_u64 v[64:65], v[166:167], 0, s[16:17]
	s_nop 0
	v_addc_co_u32_e32 v67, vcc, 0, v167, vcc
	global_load_dwordx4 v[68:71], v[66:67], off
	s_nop 0
	global_load_dwordx4 v[64:67], v[64:65], off offset:256
	v_add_f32_e32 v49, 1.0, v49
	v_rcp_f32_e32 v52, v49
	v_mul_f32_e32 v49, 0xbfb8aa3b, v55
	v_exp_f32_e32 v49, v49
	v_exp_f32_e32 v50, v50
	v_exp_f32_e32 v51, v51
	v_lshlrev_b32_e32 v54, 16, v85
	v_add_f32_e32 v49, 1.0, v49
	v_rcp_f32_e32 v53, v49
	v_add_f32_e32 v50, 1.0, v50
	v_add_f32_e32 v51, 1.0, v51
	v_rcp_f32_e32 v50, v50
	v_rcp_f32_e32 v51, v51
	v_and_b32_e32 v55, 0xffff0000, v85
	v_pk_mul_f32 v[52:53], v[52:53], v[54:55]
	v_lshlrev_b32_e32 v54, 16, v87
	v_cvt_pk_bf16_f32 v49, v52, v53
	v_lshlrev_b32_e32 v52, 16, v86
	v_and_b32_e32 v53, 0xffff0000, v86
	v_pk_mul_f32 v[50:51], v[50:51], v[52:53]
	v_and_b32_e32 v55, 0xffff0000, v87
	v_cvt_pk_bf16_f32 v50, v50, v51
	v_mul_f32_e32 v51, 0xbfb8aa3b, v72
	v_exp_f32_e32 v51, v51
	s_nop 0
	v_add_f32_e32 v51, 1.0, v51
	v_rcp_f32_e32 v52, v51
	v_mul_f32_e32 v51, 0xbfb8aa3b, v73
	v_exp_f32_e32 v51, v51
	s_nop 0
	v_add_f32_e32 v51, 1.0, v51
	v_rcp_f32_e32 v53, v51
	s_nop 0
	v_pk_mul_f32 v[52:53], v[52:53], v[54:55]
	v_add_co_u32_e32 v54, vcc, s2, v148
	v_cvt_pk_bf16_f32 v51, v52, v53
	s_nop 0
	v_addc_co_u32_e32 v55, vcc, 0, v149, vcc
	global_store_dwordx4 v[54:55], v[48:51], off
	v_lshl_add_u64 v[52:53], v[148:149], 0, s[18:19]
	s_mov_b32 s2, 0x58000
	v_pk_add_f32 v[48:49], v[34:35], v[42:43]
	v_pk_add_f32 v[34:35], v[32:33], v[40:41]
	v_mul_f32_e32 v32, 0xbfb8aa3b, v36
	v_mul_f32_e32 v33, 0xbfb8aa3b, v37
	v_exp_f32_e32 v32, v32
	v_exp_f32_e32 v33, v33
	v_lshlrev_b32_e32 v36, 16, v80
	v_and_b32_e32 v37, 0xffff0000, v80
	v_add_f32_e32 v32, 1.0, v32
	v_add_f32_e32 v33, 1.0, v33
	v_rcp_f32_e32 v32, v32
	v_rcp_f32_e32 v33, v33
	v_mul_f32_e32 v34, 0xbfb8aa3b, v34
	v_mul_f32_e32 v35, 0xbfb8aa3b, v35
	v_exp_f32_e32 v34, v34
	v_pk_mul_f32 v[32:33], v[32:33], v[36:37]
	v_exp_f32_e32 v35, v35
	v_cvt_pk_bf16_f32 v32, v32, v33
	v_mul_f32_e32 v33, 0xbfb8aa3b, v38
	v_exp_f32_e32 v33, v33
	v_add_f32_e32 v34, 1.0, v34
	v_add_f32_e32 v35, 1.0, v35
	v_rcp_f32_e32 v34, v34
	v_add_f32_e32 v33, 1.0, v33
	v_rcp_f32_e32 v36, v33
	v_mul_f32_e32 v33, 0xbfb8aa3b, v39
	v_exp_f32_e32 v33, v33
	v_rcp_f32_e32 v35, v35
	v_lshlrev_b32_e32 v38, 16, v81
	v_and_b32_e32 v39, 0xffff0000, v81
	v_add_f32_e32 v33, 1.0, v33
	v_rcp_f32_e32 v37, v33
	s_mov_b64 s[18:19], 0x58000
	v_pk_mul_f32 v[36:37], v[36:37], v[38:39]
	s_nop 0
	v_cvt_pk_bf16_f32 v33, v36, v37
	v_lshlrev_b32_e32 v36, 16, v82
	v_and_b32_e32 v37, 0xffff0000, v82
	v_pk_mul_f32 v[34:35], v[34:35], v[36:37]
	v_lshlrev_b32_e32 v38, 16, v83
	v_cvt_pk_bf16_f32 v34, v34, v35
	v_mul_f32_e32 v35, 0xbfb8aa3b, v48
	v_exp_f32_e32 v35, v35
	v_and_b32_e32 v39, 0xffff0000, v83
	v_add_f32_e32 v35, 1.0, v35
	v_rcp_f32_e32 v36, v35
	v_mul_f32_e32 v35, 0xbfb8aa3b, v49
	v_pk_add_f32 v[48:49], v[26:27], v[58:59]
	v_pk_add_f32 v[26:27], v[24:25], v[56:57]
	v_mul_f32_e32 v24, 0xbfb8aa3b, v28
	v_mul_f32_e32 v25, 0xbfb8aa3b, v29
	v_exp_f32_e32 v24, v24
	v_exp_f32_e32 v25, v25
	s_waitcnt vmcnt(1) lgkmcnt(0)
; __device__ __forceinline__ unsigned cvt_pk_bf16(float lo, float hi) { f32x2 v = {lo, hi}; bf16x2_t b = __builtin_convertvector(v, bf16x2_t); return __builtin_bit_cast(unsigned, b); }
; __device__ __forceinline__ float bflo(unsigned w) { return __uint_as_float(w << 16); }
; __device__ __forceinline__ float bfhi(unsigned w) { return __uint_as_float(w & 0xffff0000u); }
; __device__ __forceinline__ float sigmoidf_(float v) { return __builtin_amdgcn_rcpf(1.0f + __builtin_amdgcn_exp2f(-1.4426950408889634f * v)); }
;     __device__ __forceinline__ void operator()(const f32x4 (&acc)[2][2][4][2], const Unit& u, int wr, int wc, int fr, int fq) const {
;     ...
;         for (int g = 0; g < 8; ++g) {
;             const int ai = g >> 2, m = g & 3;
;             const size_t row = (size_t)256 * u.pm + 128 * ai + 64 * wr + 16 * m + fr;
;             if (g + 1 < 8) {
;                 const size_t rn = (size_t)256 * u.pm + 128 * ((g + 1) >> 2) + 64 * wr + 16 * ((g + 1) & 3) + fr;
; #pragma unroll
;                 for (int bj = 0; bj < 2; ++bj) gpre[(g + 1) & 1][bj] = *(const u32x4*)(GACT + rn * 1024 + col0 + 128 * bj);
;             }
;             asm volatile("" ::: "memory");
; #pragma unroll
;             for (int bj = 0; bj < 2; ++bj) {
;                 const u32x4 gv = gpre[g & 1][bj];
;                 const f32x4 a = acc[ai][bj][m][0] + bv[bj][0], b = acc[ai][bj][m][1] + bv[bj][1];
;                 u32x4 w;
;                 w.x = cvt_pk_bf16(bflo(gv.x) * sigmoidf_(a[0]), bfhi(gv.x) * sigmoidf_(a[1])); w.y = cvt_pk_bf16(bflo(gv.y) * sigmoidf_(a[2]), bfhi(gv.y) * sigmoidf_(a[3]));
;                 w.z = cvt_pk_bf16(bflo(gv.z) * sigmoidf_(b[0]), bfhi(gv.z) * sigmoidf_(b[1])); w.w = cvt_pk_bf16(bflo(gv.w) * sigmoidf_(b[2]), bfhi(gv.w) * sigmoidf_(b[3]));
;                 *(u32x4*)(YB + row * 1024 + col0 + 128 * bj) = w;
	v_lshlrev_b32_e32 v28, 16, v68
	v_and_b32_e32 v29, 0xffff0000, v68
	v_add_f32_e32 v24, 1.0, v24
	v_add_f32_e32 v25, 1.0, v25
	v_rcp_f32_e32 v24, v24
	v_rcp_f32_e32 v25, v25
	v_exp_f32_e32 v35, v35
	v_mul_f32_e32 v26, 0xbfb8aa3b, v26
	v_mul_f32_e32 v27, 0xbfb8aa3b, v27
	v_pk_mul_f32 v[24:25], v[24:25], v[28:29]
	v_add_f32_e32 v35, 1.0, v35
	v_cvt_pk_bf16_f32 v24, v24, v25
	v_mul_f32_e32 v25, 0xbfb8aa3b, v30
	v_exp_f32_e32 v25, v25
	v_rcp_f32_e32 v37, v35
	v_exp_f32_e32 v26, v26
	v_exp_f32_e32 v27, v27
	v_add_f32_e32 v25, 1.0, v25
	v_rcp_f32_e32 v28, v25
	v_mul_f32_e32 v25, 0xbfb8aa3b, v31
	v_exp_f32_e32 v25, v25
	v_pk_mul_f32 v[36:37], v[36:37], v[38:39]
	v_add_f32_e32 v26, 1.0, v26
	v_cvt_pk_bf16_f32 v35, v36, v37
	v_add_f32_e32 v25, 1.0, v25
	v_rcp_f32_e32 v29, v25
	global_store_dwordx4 v[52:53], v[32:35], off offset:256
	v_add_f32_e32 v27, 1.0, v27
	v_rcp_f32_e32 v26, v26
	v_add_co_u32_e32 v34, vcc, s2, v166
	v_lshl_add_u64 v[32:33], v[166:167], 0, s[18:19]
	s_nop 0
	v_addc_co_u32_e32 v35, vcc, 0, v167, vcc
	v_rcp_f32_e32 v27, v27
	global_load_dwordx4 v[36:39], v[34:35], off
	s_nop 0
	global_load_dwordx4 v[32:35], v[32:33], off offset:256
	v_lshlrev_b32_e32 v30, 16, v69
	v_and_b32_e32 v31, 0xffff0000, v69
	v_pk_mul_f32 v[28:29], v[28:29], v[30:31]
	v_lshlrev_b32_e32 v30, 16, v71
	v_cvt_pk_bf16_f32 v25, v28, v29
	v_lshlrev_b32_e32 v28, 16, v70
	v_and_b32_e32 v29, 0xffff0000, v70
	v_pk_mul_f32 v[26:27], v[26:27], v[28:29]
	v_and_b32_e32 v31, 0xffff0000, v71
	v_cvt_pk_bf16_f32 v26, v26, v27
	v_mul_f32_e32 v27, 0xbfb8aa3b, v48
	v_exp_f32_e32 v27, v27
	s_nop 0
	v_add_f32_e32 v27, 1.0, v27
	v_rcp_f32_e32 v28, v27
	v_mul_f32_e32 v27, 0xbfb8aa3b, v49
	v_exp_f32_e32 v27, v27
	s_nop 0
	v_add_f32_e32 v27, 1.0, v27
	v_rcp_f32_e32 v29, v27
	s_nop 0
	v_pk_mul_f32 v[28:29], v[28:29], v[30:31]
	v_add_co_u32_e32 v30, vcc, s3, v148
	v_cvt_pk_bf16_f32 v27, v28, v29
	s_nop 0
	v_addc_co_u32_e32 v31, vcc, 0, v149, vcc
	global_store_dwordx4 v[30:31], v[24:27], off
	v_lshl_add_u64 v[28:29], v[148:149], 0, s[16:17]
	s_mov_b64 s[16:17], -1
	v_pk_add_f32 v[24:25], v[18:19], v[42:43]
	v_pk_add_f32 v[18:19], v[16:17], v[40:41]
	v_mul_f32_e32 v16, 0xbfb8aa3b, v20
	v_mul_f32_e32 v17, 0xbfb8aa3b, v21
	v_exp_f32_e32 v16, v16
	v_exp_f32_e32 v17, v17
	v_lshlrev_b32_e32 v20, 16, v64
	v_and_b32_e32 v21, 0xffff0000, v64
	v_add_f32_e32 v16, 1.0, v16
	v_add_f32_e32 v17, 1.0, v17
	v_rcp_f32_e32 v16, v16
	v_rcp_f32_e32 v17, v17
	v_mul_f32_e32 v18, 0xbfb8aa3b, v18
	v_mul_f32_e32 v19, 0xbfb8aa3b, v19
	v_exp_f32_e32 v18, v18
	v_pk_mul_f32 v[16:17], v[16:17], v[20:21]
	v_exp_f32_e32 v19, v19
	v_cvt_pk_bf16_f32 v16, v16, v17
	v_mul_f32_e32 v17, 0xbfb8aa3b, v22
	v_exp_f32_e32 v17, v17
	v_add_f32_e32 v18, 1.0, v18
	v_add_f32_e32 v19, 1.0, v19
	v_rcp_f32_e32 v18, v18
	v_add_f32_e32 v17, 1.0, v17
	v_rcp_f32_e32 v20, v17
	v_mul_f32_e32 v17, 0xbfb8aa3b, v23
	v_exp_f32_e32 v17, v17
	v_rcp_f32_e32 v19, v19
	v_lshlrev_b32_e32 v22, 16, v65
	v_and_b32_e32 v23, 0xffff0000, v65
	v_add_f32_e32 v17, 1.0, v17
	v_rcp_f32_e32 v21, v17
	s_nop 0
	v_pk_mul_f32 v[20:21], v[20:21], v[22:23]
	s_nop 0
	v_cvt_pk_bf16_f32 v17, v20, v21
	v_lshlrev_b32_e32 v20, 16, v66
	v_and_b32_e32 v21, 0xffff0000, v66
	v_pk_mul_f32 v[18:19], v[18:19], v[20:21]
	v_lshlrev_b32_e32 v22, 16, v67
	v_cvt_pk_bf16_f32 v18, v18, v19
	v_mul_f32_e32 v19, 0xbfb8aa3b, v24
	v_exp_f32_e32 v19, v19
	v_and_b32_e32 v23, 0xffff0000, v67
	v_add_f32_e32 v19, 1.0, v19
	v_rcp_f32_e32 v20, v19
	v_mul_f32_e32 v19, 0xbfb8aa3b, v25
	v_exp_f32_e32 v19, v19
	s_nop 0
	v_add_f32_e32 v19, 1.0, v19
	v_rcp_f32_e32 v21, v19
	s_nop 0
	v_pk_mul_f32 v[20:21], v[20:21], v[22:23]
	s_nop 0
	v_cvt_pk_bf16_f32 v19, v20, v21
	global_store_dwordx4 v[28:29], v[16:19], off offset:256
	s_nop 1
	v_pk_add_f32 v[16:17], v[10:11], v[58:59]
	v_pk_add_f32 v[10:11], v[8:9], v[56:57]
	v_mul_f32_e32 v8, 0xbfb8aa3b, v12
	v_mul_f32_e32 v9, 0xbfb8aa3b, v13
	v_exp_f32_e32 v8, v8
	v_exp_f32_e32 v9, v9
	s_waitcnt vmcnt(2) lgkmcnt(0)
; __device__ __forceinline__ unsigned cvt_pk_bf16(float lo, float hi) { f32x2 v = {lo, hi}; bf16x2_t b = __builtin_convertvector(v, bf16x2_t); return __builtin_bit_cast(unsigned, b); }
; __device__ __forceinline__ float bflo(unsigned w) { return __uint_as_float(w << 16); }
; __device__ __forceinline__ float bfhi(unsigned w) { return __uint_as_float(w & 0xffff0000u); }
; __device__ __forceinline__ float sigmoidf_(float v) { return __builtin_amdgcn_rcpf(1.0f + __builtin_amdgcn_exp2f(-1.4426950408889634f * v)); }
; #define PG8_BAR __builtin_amdgcn_s_barrier()
; template <class Epi, class Sched, bool ALIGN_EPI, bool SP2, bool PERMA = false>
; __device__ __forceinline__ void gemm_phase(LAS unsigned char* lds, const int tid, const int lda, const int ldb, const Sched& S, const Epi& E) {
;     ...
;         if (!has_next) break;
; #pragma unroll
;         for (int a = 0; a < 2; ++a)
; #pragma unroll
;             for (int b = 0; b < 2; ++b)
; #pragma unroll
;                 for (int m = 0; m < 4; ++m)
; #pragma unroll
;                     for (int n = 0; n < 2; ++n) acc[a][b][m][n] = (f32x4){0.f, 0.f, 0.f, 0.f};
;         cur = nxt; cA = nA; cB = nB; ++ui;
;         if constexpr (ALIGN_EPI) { if (wr == 1) PG8_BAR; }
;     __device__ __forceinline__ void operator()(const f32x4 (&acc)[2][2][4][2], const Unit& u, int wr, int wc, int fr, int fq) const {
;     ...
;             for (int bj = 0; bj < 2; ++bj) {
;                 const u32x4 gv = gpre[g & 1][bj];
;                 const f32x4 a = acc[ai][bj][m][0] + bv[bj][0], b = acc[ai][bj][m][1] + bv[bj][1];
;                 u32x4 w;
;                 w.x = cvt_pk_bf16(bflo(gv.x) * sigmoidf_(a[0]), bfhi(gv.x) * sigmoidf_(a[1])); w.y = cvt_pk_bf16(bflo(gv.y) * sigmoidf_(a[2]), bfhi(gv.y) * sigmoidf_(a[3]));
;                 w.z = cvt_pk_bf16(bflo(gv.z) * sigmoidf_(b[0]), bfhi(gv.z) * sigmoidf_(b[1])); w.w = cvt_pk_bf16(bflo(gv.w) * sigmoidf_(b[2]), bfhi(gv.w) * sigmoidf_(b[3]));
;                 *(u32x4*)(YB + row * 1024 + col0 + 128 * bj) = w;
	v_lshlrev_b32_e32 v12, 16, v36
	v_and_b32_e32 v13, 0xffff0000, v36
	v_add_f32_e32 v8, 1.0, v8
	v_add_f32_e32 v9, 1.0, v9
	v_rcp_f32_e32 v8, v8
	v_rcp_f32_e32 v9, v9
	v_mul_f32_e32 v10, 0xbfb8aa3b, v10
	v_mul_f32_e32 v11, 0xbfb8aa3b, v11
	v_exp_f32_e32 v10, v10
	v_pk_mul_f32 v[8:9], v[8:9], v[12:13]
	v_exp_f32_e32 v11, v11
	v_cvt_pk_bf16_f32 v8, v8, v9
	v_mul_f32_e32 v9, 0xbfb8aa3b, v14
	v_exp_f32_e32 v9, v9
	v_add_f32_e32 v10, 1.0, v10
	v_add_f32_e32 v11, 1.0, v11
	v_rcp_f32_e32 v10, v10
	v_add_f32_e32 v9, 1.0, v9
	v_rcp_f32_e32 v12, v9
	v_mul_f32_e32 v9, 0xbfb8aa3b, v15
	v_exp_f32_e32 v9, v9
	v_rcp_f32_e32 v11, v11
	v_lshlrev_b32_e32 v14, 16, v37
	v_and_b32_e32 v15, 0xffff0000, v37
	v_add_f32_e32 v9, 1.0, v9
	v_rcp_f32_e32 v13, v9
	s_nop 0
	v_pk_mul_f32 v[12:13], v[12:13], v[14:15]
	s_nop 0
	v_cvt_pk_bf16_f32 v9, v12, v13
	v_lshlrev_b32_e32 v12, 16, v38
	v_and_b32_e32 v13, 0xffff0000, v38
	v_pk_mul_f32 v[10:11], v[10:11], v[12:13]
	v_lshlrev_b32_e32 v14, 16, v39
	v_cvt_pk_bf16_f32 v10, v10, v11
	v_mul_f32_e32 v11, 0xbfb8aa3b, v16
	v_exp_f32_e32 v11, v11
	v_and_b32_e32 v15, 0xffff0000, v39
	v_add_f32_e32 v11, 1.0, v11
	v_rcp_f32_e32 v12, v11
	v_mul_f32_e32 v11, 0xbfb8aa3b, v17
	v_exp_f32_e32 v11, v11
	s_nop 0
	v_add_f32_e32 v11, 1.0, v11
	v_rcp_f32_e32 v13, v11
	s_nop 0
	v_pk_mul_f32 v[12:13], v[12:13], v[14:15]
	v_add_co_u32_e32 v14, vcc, s2, v148
	v_cvt_pk_bf16_f32 v11, v12, v13
	s_nop 0
	v_addc_co_u32_e32 v15, vcc, 0, v149, vcc
	global_store_dwordx4 v[14:15], v[8:11], off
	v_lshl_add_u64 v[12:13], v[148:149], 0, s[18:19]
	s_andn2_b64 vcc, exec, s[14:15]
	v_pk_add_f32 v[8:9], v[2:3], v[42:43]
	v_pk_add_f32 v[2:3], v[0:1], v[40:41]
	v_mul_f32_e32 v0, 0xbfb8aa3b, v4
	v_mul_f32_e32 v1, 0xbfb8aa3b, v5
	v_exp_f32_e32 v0, v0
	v_exp_f32_e32 v1, v1
	v_lshlrev_b32_e32 v4, 16, v32
	v_and_b32_e32 v5, 0xffff0000, v32
	v_add_f32_e32 v0, 1.0, v0
	v_add_f32_e32 v1, 1.0, v1
	v_rcp_f32_e32 v0, v0
	v_rcp_f32_e32 v1, v1
	v_mul_f32_e32 v2, 0xbfb8aa3b, v2
	v_mul_f32_e32 v3, 0xbfb8aa3b, v3
	v_exp_f32_e32 v2, v2
	v_pk_mul_f32 v[0:1], v[0:1], v[4:5]
	v_exp_f32_e32 v3, v3
	v_cvt_pk_bf16_f32 v0, v0, v1
	v_mul_f32_e32 v1, 0xbfb8aa3b, v6
	v_exp_f32_e32 v1, v1
	v_add_f32_e32 v2, 1.0, v2
	v_add_f32_e32 v3, 1.0, v3
	v_rcp_f32_e32 v2, v2
	v_add_f32_e32 v1, 1.0, v1
	v_rcp_f32_e32 v4, v1
	v_mul_f32_e32 v1, 0xbfb8aa3b, v7
	v_exp_f32_e32 v1, v1
	v_rcp_f32_e32 v3, v3
	v_lshlrev_b32_e32 v6, 16, v33
	v_and_b32_e32 v7, 0xffff0000, v33
	v_add_f32_e32 v1, 1.0, v1
	v_rcp_f32_e32 v5, v1
	s_nop 0
	v_pk_mul_f32 v[4:5], v[4:5], v[6:7]
	s_nop 0
	v_cvt_pk_bf16_f32 v1, v4, v5
	v_lshlrev_b32_e32 v4, 16, v34
	v_and_b32_e32 v5, 0xffff0000, v34
	v_pk_mul_f32 v[2:3], v[2:3], v[4:5]
	v_lshlrev_b32_e32 v6, 16, v35
	v_cvt_pk_bf16_f32 v2, v2, v3
	v_mul_f32_e32 v3, 0xbfb8aa3b, v8
	v_exp_f32_e32 v3, v3
	v_and_b32_e32 v7, 0xffff0000, v35
	v_add_f32_e32 v3, 1.0, v3
	v_rcp_f32_e32 v4, v3
	v_mul_f32_e32 v3, 0xbfb8aa3b, v9
	v_exp_f32_e32 v3, v3
	s_nop 0
	v_add_f32_e32 v3, 1.0, v3
	v_rcp_f32_e32 v5, v3
	s_nop 0
	v_pk_mul_f32 v[4:5], v[4:5], v[6:7]
	s_nop 0
	v_cvt_pk_bf16_f32 v3, v4, v5
	global_store_dwordx4 v[12:13], v[0:3], off offset:256
	s_cbranch_vccnz .LBB0_380
	v_readlane_b32 s2, v254, 47
	v_readlane_b32 s3, v254, 48
	s_andn2_b64 vcc, exec, s[2:3]
	s_cbranch_vccnz .LBB0_379
	s_barrier
	s_branch .LBB0_379
